# hoist all global loads of the P3/P4/P5 sample-row tail sections to the section top (fresh registers, recomputed vmcnt waits)
# speedup vs baseline: 1.0504x; 1.0059x over previous
; #define LAS __attribute__((address_space(3)))
; __device__ __forceinline__ int permrow(int n) { return (n & ~255) | ((((n >> 5) & 1) * 128) + (((n >> 6) & 3) * 32) + (n & 31)); }
; template <int KSTEPS>
; __device__ __forceinline__ void tail_partial(const bf16_t* A, int lda, const bf16_t* Bt, int ldb, int col0, LAS float* part, int lane) {
;     const int fr = lane & 15, fq = lane >> 4;
;     f32x4 acc[2][4];
; #pragma unroll
;     for (int m = 0; m < 2; ++m)
; #pragma unroll
;         for (int n = 0; n < 4; ++n) acc[m][n] = (f32x4){0.f, 0.f, 0.f, 0.f};
;     const bf16_t* ap = A + (size_t)fr * lda + 8 * fq;
;     const bf16_t* bp[4];
; #pragma unroll
;     for (int n = 0; n < 4; ++n) bp[n] = Bt + (size_t)permrow(col0 + 16 * n + fr) * ldb + 8 * fq;
; #pragma unroll
;     for (int ks = 0; ks < KSTEPS; ++ks) {
;         bf16x8 a[2], b[4];
; #pragma unroll
;         for (int m = 0; m < 2; ++m) a[m] = *(const bf16x8*)(ap + (size_t)(16 * m) * lda + 32 * ks);
; #pragma unroll
;         for (int n = 0; n < 4; ++n) b[n] = *(const bf16x8*)(bp[n] + 32 * ks);
; __global__ void __launch_bounds__(NWAVES * 64, 2) fwd_megakernel(Args args) {
;     ...
;             const int tm = bx >> 4, tn = bx & 15, row0 = MP + 32 * tm, col0 = 64 * tn, br = wave >> 2, kw = (wave & 3) * 128;
;             LAS float* parts = (LAS float*)lds;
;             tail_partial<4>(U + (size_t)row0 * LDU + (br ? C_QB : C_QA) + kw, LDU, WO_t + br * 512 + kw, DM, col0, parts + wave * 2048, lane);
.LBB0_710:
	s_or_b64 exec, exec, s[0:1]
	v_readlane_b32 s2, v254, 19
	s_lshl_b32 s92, s94, 1
	v_readlane_b32 s3, v254, 20
	s_andn2_b32 s92, s92, 31
	s_lshl_b32 s23, s94, 6
	s_waitcnt lgkmcnt(0)
	v_cndmask_b32_e64 v1, 0, 1, s[2:3]
	s_mov_b32 s0, 0x8000
	s_add_i32 s84, s92, 0x8000
	s_and_b32 s22, s23, 0x3c0
	v_cmp_ne_u32_e64 s[38:39], 1, v1
	s_andn2_b64 vcc, exec, s[2:3]
	s_movk_i32 s85, 0x82
	s_barrier
	s_cbranch_vccnz .LBB0_712
	s_lshr_b32 s10, s23, 1
	s_and_b32 s11, s10, 0x60
	s_mul_i32 s10, s84, 0x2a00
	v_mov_b32_e32 v40, v0
	s_mul_hi_i32 s12, s84, 0x2a00
	s_add_u32 s13, s82, s10
	s_addc_u32 s10, s83, s12
	v_readfirstlane_b32 s12, v40
	s_ashr_i32 s14, s12, 6
	s_cmpk_lt_u32 s12, 0x100
	s_cselect_b32 s15, 0, 0xa00
	s_add_u32 s16, s13, s15
	s_addc_u32 s13, s10, 0
	s_lshl_b32 s10, s14, 8
	s_and_b32 s14, s10, 0x300
	s_add_u32 s18, s16, s14
	s_addc_u32 s19, s13, 0
	s_lshl_b32 s10, s12, 1
	s_and_b32 s12, s10, 0xfffffe00
	s_ashr_i32 s13, s12, 31
	s_lshl_b64 s[16:17], s[12:13], 1
	s_add_u32 s10, s8, s16
	s_addc_u32 s12, s9, s17
	s_add_u32 s16, s10, s14
	v_and_b32_e32 v41, 15, v40
	s_addc_u32 s17, s12, 0
	v_mul_u32_u24_e32 v42, 0x1500, v41
	v_and_b32_e32 v44, 48, v40
	v_mov_b32_e32 v45, 0
	v_lshl_add_u64 v[50:51], s[16:17], 0, v[44:45]
	s_and_b32 s10, s23, 0x300
	v_lshlrev_b32_e32 v52, 1, v42
	v_mov_b32_e32 v53, v45
	s_or_b32 s12, s10, s11
	v_lshl_add_u64 v[42:43], s[18:19], 0, v[52:53]
	v_or_b32_e32 v52, s12, v41
	v_lshl_add_u64 v[58:59], v[42:43], 0, v[44:45]
	s_mov_b32 s10, 0x2a000
	v_lshlrev_b32_e32 v42, 11, v52
	v_mov_b32_e32 v43, v45
	v_add_co_u32_e32 v52, vcc, s10, v58
	s_nop 1
	v_lshl_add_u64 v[60:61], v[50:51], 0, v[42:43]
	v_addc_co_u32_e32 v53, vcc, 0, v59, vcc
	s_nop 1
	v_add_co_u32_e32 v42, vcc, s0, v60
	s_nop 1
	s_mov_b32 s10, 0x40000
	v_addc_co_u32_e32 v43, vcc, 0, v61, vcc
	s_nop 1
	v_add_co_u32_e32 v50, vcc, s10, v60
	s_nop 1
	global_load_dwordx4 v[64:67], v[60:61], off
	global_load_dwordx4 v[68:71], v[60:61], off offset:64
	v_addc_co_u32_e32 v51, vcc, 0, v61, vcc
	s_nop 1
	global_load_dwordx4 v[72:75], v[52:53], off
	global_load_dwordx4 v[84:87], v[42:43], off
	global_load_dwordx4 v[88:91], v[50:51], off
	s_mov_b32 s10, 0x48000
	v_add_co_u32_e32 v62, vcc, s10, v60
	s_nop 1
	global_load_dwordx4 v[92:95], v[58:59], off
	global_load_dwordx4 v[96:99], v[58:59], off offset:64
	v_addc_co_u32_e32 v63, vcc, 0, v61, vcc
	s_nop 1
	global_load_dwordx4 v[100:103], v[62:63], off
	global_load_dwordx4 v[104:107], v[52:53], off offset:64
	global_load_dwordx4 v[108:111], v[42:43], off offset:64
	global_load_dwordx4 v[112:115], v[50:51], off offset:64
	global_load_dwordx4 v[116:119], v[62:63], off offset:64
	s_movk_i32 s10, 0x2a00
	global_load_dwordx4 v[120:123], v[60:61], off offset:128
	global_load_dwordx4 v[124:127], v[58:59], off offset:128
	global_load_dwordx4 v[128:131], v[52:53], off offset:128
	global_load_dwordx4 v[132:135], v[42:43], off offset:128
	global_load_dwordx4 v[136:139], v[50:51], off offset:128
	global_load_dwordx4 v[140:143], v[58:59], off offset:192
	global_load_dwordx4 v[144:147], v[60:61], off offset:192
	global_load_dwordx4 v[148:151], v[62:63], off offset:128
	global_load_dwordx4 v[152:155], v[52:53], off offset:192
	global_load_dwordx4 v[156:159], v[62:63], off offset:192
	global_load_dwordx4 v[60:63], v[42:43], off offset:192
	global_load_dwordx4 v[160:163], v[50:51], off offset:192
	v_ashrrev_i32_e32 v41, 4, v40
	v_lshlrev_b32_e32 v42, 2, v40
	v_add_u32_e32 v40, s84, v41
	v_and_or_b32 v41, v42, 60, s22
	v_mov_b64_e32 v[42:43], s[82:83]
	v_mad_i64_i32 v[50:51], s[12:13], v40, s10, v[42:43]
	v_lshlrev_b32_e32 v40, 1, v41
	v_mov_b32_e32 v42, v40
	v_mov_b32_e32 v43, v45
	v_lshl_add_u64 v[52:53], v[50:51], 0, v[42:43]
	s_movk_i32 s10, 0x1000
	v_add_co_u32_e32 v40, vcc, s10, v52
	s_nop 1
	s_movk_i32 s10, 0x2000
	v_addc_co_u32_e32 v41, vcc, 0, v53, vcc
	s_nop 1
	v_add_co_u32_e32 v42, vcc, s10, v52
	s_nop 1
	v_addc_co_u32_e32 v43, vcc, 0, v53, vcc
	s_nop 1
	global_load_dwordx2 v[44:45], v[40:41], off offset:2560
	global_load_dwordx2 v[40:41], v[42:43], off offset:512
	s_nop 0
	s_nop 0
	s_nop 0
	v_mov_b32_e32 v1, v0
	s_nop 0
	s_nop 0
	s_nop 0
	v_readfirstlane_b32 s4, v1
	s_ashr_i32 s6, s4, 6
	s_nop 0
	s_nop 0
	s_nop 0
	s_nop 0
	s_nop 0
	s_nop 0
	s_nop 0
	s_nop 0
	s_nop 0
	s_nop 0
	s_nop 0
	s_nop 0
	s_nop 0
	s_nop 0
	s_nop 0
	v_and_b32_e32 v80, 15, v1
	s_nop 0
	s_nop 0
	v_and_b32_e32 v78, 48, v1
	v_mov_b32_e32 v79, 0
	s_nop 0
	s_nop 0
	s_nop 0
	s_nop 0
	s_nop 0
	s_nop 0
	s_nop 0
	s_nop 0
	s_nop 0
	s_nop 0
	s_nop 0
	s_nop 0
	s_nop 0
	s_nop 0
	s_nop 0
	s_nop 0
	s_nop 0
	s_nop 0
	s_nop 0
	s_nop 0
	s_nop 0
	s_nop 0
	s_nop 0
	s_nop 0
	s_nop 0
	s_nop 0
	s_nop 0
	s_nop 0
	s_nop 0
	s_nop 0
	s_nop 0
	s_nop 0
	s_nop 0
	s_nop 0
	s_nop 0
	s_nop 0
	s_lshl_b32 s1, s6, 13
	s_add_i32 s1, s1, 0
	s_nop 0
	s_movk_i32 s85, 0x80
	s_nop 0
	s_waitcnt vmcnt(20)
	v_mfma_f32_16x16x32_bf16 v[30:33], v[64:67], v[92:95], 0
	v_mfma_f32_16x16x32_bf16 v[2:5], v[64:67], v[72:75], 0
	v_mfma_f32_16x16x32_bf16 v[46:49], v[84:87], v[92:95], 0
	v_mfma_f32_16x16x32_bf16 v[54:57], v[88:91], v[92:95], 0
	s_nop 0
	s_waitcnt vmcnt(18)
; #define LAS __attribute__((address_space(3)))
; __device__ __forceinline__ unsigned cvt_pk_bf16(float lo, float hi) { const f32x2_t v = {lo, hi}; const bf16x2_t b = __builtin_convertvector(v, bf16x2_t); return __builtin_bit_cast(unsigned, b); }
; __device__ __forceinline__ float bf_lo(unsigned w) { return __uint_as_float(w << 16); }
; __device__ __forceinline__ float bf_hi(unsigned w) { return __uint_as_float(w & 0xffff0000u); }
; template <int KSTEPS>
; __device__ __forceinline__ void tail_partial(const bf16_t* A, int lda, const bf16_t* Bt, int ldb, int col0, LAS float* part, int lane) {
;     ...
;     for (int ks = 0; ks < KSTEPS; ++ks) {
;         bf16x8 a[2], b[4];
; #pragma unroll
;         for (int m = 0; m < 2; ++m) a[m] = *(const bf16x8*)(ap + (size_t)(16 * m) * lda + 32 * ks);
; #pragma unroll
;         for (int n = 0; n < 4; ++n) b[n] = *(const bf16x8*)(bp[n] + 32 * ks);
; #pragma unroll
;         for (int m = 0; m < 2; ++m)
; #pragma unroll
;             for (int n = 0; n < 4; ++n) acc[m][n] = __builtin_amdgcn_mfma_f32_16x16x32_bf16(b[n], a[m], acc[m][n], 0, 0, 0);
;     }
; #pragma unroll
;     for (int m = 0; m < 2; ++m)
; #pragma unroll
;         for (int n = 0; n < 4; ++n) *(LAS f32x4*)(part + (16 * m + fr) * 64 + 16 * n + 4 * fq) = acc[m][n];
; __global__ void __launch_bounds__(NWAVES * 64, 2) fwd_megakernel(Args args) {
;     ...
;             const f32x4 ca = tail_sum(parts, 0, 4, tid), cb = tail_sum(parts, 4, 8, tid);
;             const int r = row0 + (tid >> 4), c = col0 + (tid & 15) * 4;
;             const u32x2 ga = *(const u32x2*)(U + (size_t)r * LDU + C_GA + c), gb = *(const u32x2*)(U + (size_t)r * LDU + C_GB + c);
;             u32x2 w;
;             w.x = cvt_pk_bf16(bf_lo(ga.x) * ca[0] + bf_lo(gb.x) * cb[0], bf_hi(ga.x) * ca[1] + bf_hi(gb.x) * cb[1]);
;             w.y = cvt_pk_bf16(bf_lo(ga.y) * ca[2] + bf_lo(gb.y) * cb[2], bf_hi(ga.y) * ca[3] + bf_hi(gb.y) * cb[3]);
;             *(u32x2*)(R1 + (size_t)r * DM + c) = w;
	v_mfma_f32_16x16x32_bf16 v[6:9], v[100:103], v[92:95], 0
	v_mfma_f32_16x16x32_bf16 v[14:17], v[84:87], v[72:75], 0
	v_mfma_f32_16x16x32_bf16 v[18:21], v[88:91], v[72:75], 0
	v_mfma_f32_16x16x32_bf16 v[10:13], v[100:103], v[72:75], 0
	v_mfma_f32_16x16x32_bf16 v[30:33], v[68:71], v[96:99], v[30:33]
	s_nop 0
	s_waitcnt vmcnt(17)
	v_mfma_f32_16x16x32_bf16 v[2:5], v[68:71], v[104:107], v[2:5]
	s_nop 0
	s_waitcnt vmcnt(16)
	v_mfma_f32_16x16x32_bf16 v[26:29], v[108:111], v[96:99], v[46:49]
	s_nop 0
	s_waitcnt vmcnt(15)
	v_mfma_f32_16x16x32_bf16 v[34:37], v[112:115], v[96:99], v[54:57]
	s_nop 0
	s_waitcnt vmcnt(14)
	v_mfma_f32_16x16x32_bf16 v[6:9], v[116:119], v[96:99], v[6:9]
	s_nop 0
	v_mfma_f32_16x16x32_bf16 v[14:17], v[108:111], v[104:107], v[14:17]
	s_nop 0
	s_nop 0
	v_mfma_f32_16x16x32_bf16 v[18:21], v[112:115], v[104:107], v[18:21]
	s_nop 0
	v_mfma_f32_16x16x32_bf16 v[10:13], v[116:119], v[104:107], v[10:13]
	s_nop 0
	s_nop 0
	s_nop 0
	s_nop 0
	s_nop 0
	s_nop 0
	s_nop 0
	s_nop 0
	s_waitcnt vmcnt(12)
	v_mfma_f32_16x16x32_bf16 v[30:33], v[120:123], v[124:127], v[30:33]
	s_nop 0
	s_nop 0
	s_waitcnt vmcnt(11)
	v_mfma_f32_16x16x32_bf16 v[2:5], v[120:123], v[128:131], v[2:5]
	s_nop 0
	s_nop 0
	s_nop 0
	s_nop 0
	s_waitcnt vmcnt(10)
	v_mfma_f32_16x16x32_bf16 v[26:29], v[132:135], v[124:127], v[26:29]
	s_nop 0
	s_waitcnt vmcnt(9)
	v_mfma_f32_16x16x32_bf16 v[34:37], v[136:139], v[124:127], v[34:37]
	s_nop 0
	s_waitcnt vmcnt(6)
	v_mfma_f32_16x16x32_bf16 v[6:9], v[148:151], v[124:127], v[6:9]
	v_mfma_f32_16x16x32_bf16 v[14:17], v[132:135], v[128:131], v[14:17]
	v_mfma_f32_16x16x32_bf16 v[18:21], v[136:139], v[128:131], v[18:21]
	v_lshlrev_b32_e32 v38, 8, v80
	v_mfma_f32_16x16x32_bf16 v[10:13], v[148:151], v[128:131], v[10:13]
	v_mfma_f32_16x16x32_bf16 v[30:33], v[144:147], v[140:143], v[30:33]
	s_nop 0
	s_waitcnt vmcnt(3)
	v_mfma_f32_16x16x32_bf16 v[26:29], v[60:63], v[140:143], v[26:29]
	s_nop 0
	s_waitcnt vmcnt(2)
	v_mfma_f32_16x16x32_bf16 v[34:37], v[160:163], v[140:143], v[34:37]
	v_mfma_f32_16x16x32_bf16 v[6:9], v[156:159], v[140:143], v[6:9]
	v_mfma_f32_16x16x32_bf16 v[2:5], v[144:147], v[152:155], v[2:5]
	v_mfma_f32_16x16x32_bf16 v[14:17], v[60:63], v[152:155], v[14:17]
	v_add3_u32 v22, s1, v38, v78
	ds_write_b128 v22, v[30:33]
	s_nop 0
	ds_write_b128 v22, v[26:29] offset:64
	s_nop 0
	ds_write_b128 v22, v[34:37] offset:128
	ds_write_b128 v22, v[6:9] offset:192
	ds_write_b128 v22, v[2:5] offset:4096
	ds_write_b128 v22, v[14:17] offset:4160
	v_mfma_f32_16x16x32_bf16 v[18:21], v[160:163], v[152:155], v[18:21]
	v_mfma_f32_16x16x32_bf16 v[2:5], v[156:159], v[152:155], v[10:13]
	s_nop 6
	ds_write_b128 v22, v[18:21] offset:4224
	ds_write_b128 v22, v[2:5] offset:4288
	v_ashrrev_i32_e32 v2, 4, v1
	v_lshlrev_b32_e32 v3, 2, v1
	v_add_u32_e32 v2, s84, v2
	v_and_or_b32 v3, v3, 60, s22
	s_nop 0
	s_nop 0
	v_lshlrev_b32_e32 v78, 1, v3
	s_nop 0
	s_nop 0
	s_nop 0
	s_nop 0
	s_nop 0
	s_nop 0
	s_nop 0
	s_waitcnt lgkmcnt(0)
	s_nop 0
	s_nop 0
	s_barrier
	s_nop 0
	s_nop 0
	v_ashrrev_i32_e32 v3, 31, v2
	v_lshlrev_b64 v[2:3], 11, v[2:3]
	v_lshl_add_u32 v1, v1, 4, 0
	v_lshl_add_u64 v[2:3], s[80:81], 0, v[2:3]
	v_lshl_add_u64 v[38:39], v[2:3], 0, v[78:79]
	ds_read_b128 v[2:5], v1
	ds_read_b128 v[6:9], v1 offset:8192
	ds_read_b128 v[10:13], v1 offset:32768
	ds_read_b128 v[14:17], v1 offset:16384
	ds_read_b128 v[18:21], v1 offset:24576
	ds_read_b128 v[22:25], v1 offset:40960
	ds_read_b128 v[26:29], v1 offset:49152
	ds_read_b128 v[30:33], v1 offset:57344
	s_waitcnt lgkmcnt(5)
	v_pk_add_f32 v[12:13], v[12:13], 0 op_sel_hi:[1,0]
	v_pk_add_f32 v[10:11], v[10:11], 0 op_sel_hi:[1,0]
	v_pk_add_f32 v[4:5], v[4:5], 0 op_sel_hi:[1,0]
	v_pk_add_f32 v[2:3], v[2:3], 0 op_sel_hi:[1,0]
	s_waitcnt lgkmcnt(2)
	v_pk_add_f32 v[12:13], v[12:13], v[24:25]
	v_pk_add_f32 v[10:11], v[10:11], v[22:23]
	v_pk_add_f32 v[4:5], v[4:5], v[8:9]
	v_pk_add_f32 v[2:3], v[2:3], v[6:7]
	s_waitcnt lgkmcnt(1)
	v_pk_add_f32 v[6:7], v[12:13], v[28:29]
	v_pk_add_f32 v[8:9], v[10:11], v[26:27]
	v_pk_add_f32 v[4:5], v[4:5], v[16:17]
	v_pk_add_f32 v[2:3], v[2:3], v[14:15]
	s_waitcnt lgkmcnt(0)
	v_pk_add_f32 v[6:7], v[6:7], v[32:33]
	v_pk_add_f32 v[8:9], v[8:9], v[30:31]
	v_pk_add_f32 v[4:5], v[4:5], v[20:21]
	v_pk_add_f32 v[2:3], v[2:3], v[18:19]
	s_nop 0
	s_waitcnt vmcnt(1)
	v_lshlrev_b32_e32 v10, 16, v44
	s_nop 0
	s_waitcnt vmcnt(0)
	v_lshlrev_b32_e32 v12, 16, v40
	v_and_b32_e32 v13, 0xffff0000, v40
	v_lshlrev_b32_e32 v16, 16, v41
	v_and_b32_e32 v17, 0xffff0000, v41
	v_and_b32_e32 v11, 0xffff0000, v44
	v_lshlrev_b32_e32 v14, 16, v45
	v_and_b32_e32 v15, 0xffff0000, v45
	v_pk_mul_f32 v[8:9], v[8:9], v[12:13]
	v_pk_mul_f32 v[6:7], v[6:7], v[16:17]
	v_pk_fma_f32 v[2:3], v[2:3], v[10:11], v[8:9]
	v_pk_fma_f32 v[4:5], v[4:5], v[14:15], v[6:7]
	v_cvt_pk_bf16_f32 v2, v2, v3
	v_cvt_pk_bf16_f32 v3, v4, v5
	global_store_dwordx2 v[38:39], v[2:3], off
	s_barrier

; #define LAS __attribute__((address_space(3)))
; __device__ __forceinline__ int permrow(int n) { return (n & ~255) | ((((n >> 5) & 1) * 128) + (((n >> 6) & 3) * 32) + (n & 31)); }
; template <int KSTEPS>
; __device__ __forceinline__ void tail_partial(const bf16_t* A, int lda, const bf16_t* Bt, int ldb, int col0, LAS float* part, int lane) {
;     const int fr = lane & 15, fq = lane >> 4;
;     f32x4 acc[2][4];
; #pragma unroll
;     for (int m = 0; m < 2; ++m)
; #pragma unroll
;         for (int n = 0; n < 4; ++n) acc[m][n] = (f32x4){0.f, 0.f, 0.f, 0.f};
;     const bf16_t* ap = A + (size_t)fr * lda + 8 * fq;
;     const bf16_t* bp[4];
; #pragma unroll
;     for (int n = 0; n < 4; ++n) bp[n] = Bt + (size_t)permrow(col0 + 16 * n + fr) * ldb + 8 * fq;
; #pragma unroll
;     for (int ks = 0; ks < KSTEPS; ++ks) {
;         bf16x8 a[2], b[4];
; #pragma unroll
;         for (int m = 0; m < 2; ++m) a[m] = *(const bf16x8*)(ap + (size_t)(16 * m) * lda + 32 * ks);
; #pragma unroll
;         for (int n = 0; n < 4; ++n) b[n] = *(const bf16x8*)(bp[n] + 32 * ks);
; __global__ void __launch_bounds__(NWAVES * 64, 2) fwd_megakernel(Args args) {
;     ...
;             const int tm = bx >> 4, tn = bx & 15, row0 = MP + 32 * tm, col0 = 64 * tn, kw = wave * 128;
;             LAS float* parts = (LAS float*)lds;
;             tail_partial<4>(R1 + (size_t)row0 * DM + kw, DM, Wout_t + kw, DM, col0, parts + wave * 2048, lane);
.LBB0_884:
	v_readlane_b32 s0, v254, 19
	s_add_u32 s8, s62, 0x1400000
	v_readlane_b32 s1, v254, 20
	s_addc_u32 s9, s63, 0
	s_ashr_i32 s85, s84, 31
	s_movk_i32 s24, 0x82
	s_and_b64 vcc, exec, s[0:1]
	s_cbranch_vccz .LBB0_888
	s_and_b32 s11, s94, 15
	s_lshl_b32 s12, s11, 6
	s_lshl_b64 s[14:15], s[84:85], 11
	s_add_u32 s11, s80, s14
	s_addc_u32 s13, s81, s15
	s_lshl_b32 s14, s94, 5
	s_and_b32 s15, s14, 0x60
	s_lshl_b32 s16, s2, 7
	s_ashr_i32 s17, s16, 31
	s_lshl_b64 s[18:19], s[16:17], 1
	s_add_u32 s16, s11, s18
	s_addc_u32 s17, s13, s19
	s_add_u32 s26, s96, s18
	v_and_b32_e32 v52, 15, v1
	v_mov_b32_e32 v55, 0
	s_addc_u32 s27, s97, s19
	s_and_b32 s11, s12, 0x300
	v_lshlrev_b32_e32 v60, 11, v52
	v_mov_b32_e32 v61, v55
	v_and_b32_e32 v54, 48, v1
	s_or_b32 s13, s11, s15
	v_lshl_add_u64 v[62:63], s[16:17], 0, v[60:61]
	v_or_b32_e32 v53, s13, v52
	v_lshl_add_u64 v[60:61], v[62:63], 0, v[54:55]
	s_mov_b32 s11, 0x8000
	v_lshl_add_u64 v[62:63], s[26:27], 0, v[54:55]
	v_lshlrev_b32_e32 v64, 11, v53
	v_mov_b32_e32 v65, v55
	v_add_co_u32_e32 v66, vcc, s11, v60
	s_nop 1
	v_lshl_add_u64 v[68:69], v[62:63], 0, v[64:65]
	v_addc_co_u32_e32 v67, vcc, 0, v61, vcc
	s_nop 1
	v_add_co_u32_e32 v62, vcc, s11, v68
	s_nop 1
	s_mov_b32 s11, 0x40000
	v_addc_co_u32_e32 v63, vcc, 0, v69, vcc
	s_nop 1
	v_add_co_u32_e32 v64, vcc, s11, v68
	s_nop 1
	global_load_dwordx4 v[72:75], v[68:69], off
	global_load_dwordx4 v[76:79], v[68:69], off offset:64
	v_addc_co_u32_e32 v65, vcc, 0, v69, vcc
	s_nop 1
	global_load_dwordx4 v[84:87], v[66:67], off
	global_load_dwordx4 v[88:91], v[62:63], off
	global_load_dwordx4 v[92:95], v[64:65], off
	s_mov_b32 s11, 0x48000
	v_add_co_u32_e32 v70, vcc, s11, v68
	s_nop 1
	global_load_dwordx4 v[96:99], v[60:61], off
	global_load_dwordx4 v[100:103], v[60:61], off offset:64
	v_addc_co_u32_e32 v71, vcc, 0, v69, vcc
	s_nop 1
	global_load_dwordx4 v[104:107], v[70:71], off
	global_load_dwordx4 v[108:111], v[66:67], off offset:64
	global_load_dwordx4 v[112:115], v[62:63], off offset:64
	global_load_dwordx4 v[116:119], v[64:65], off offset:64
	global_load_dwordx4 v[120:123], v[70:71], off offset:64
	global_load_dwordx4 v[124:127], v[68:69], off offset:128
	global_load_dwordx4 v[128:131], v[60:61], off offset:128
	global_load_dwordx4 v[132:135], v[66:67], off offset:128
	global_load_dwordx4 v[136:139], v[62:63], off offset:128
	global_load_dwordx4 v[140:143], v[64:65], off offset:128
	global_load_dwordx4 v[144:147], v[60:61], off offset:192
	global_load_dwordx4 v[148:151], v[68:69], off offset:192
	global_load_dwordx4 v[152:155], v[70:71], off offset:128
	global_load_dwordx4 v[156:159], v[66:67], off offset:192
	global_load_dwordx4 v[160:163], v[70:71], off offset:192
	global_load_dwordx4 v[68:71], v[62:63], off offset:192
	global_load_dwordx4 v[60:63], v[64:65], off offset:192
	v_lshl_or_b32 v53, v52, 2, s12
	v_ashrrev_i32_e32 v52, 4, v1
	v_add_u32_e32 v64, s92, v52
	v_ashrrev_i32_e32 v65, 31, v64
	v_lshlrev_b64 v[66:67], 12, v[64:65]
	v_lshl_add_u64 v[64:65], s[66:67], 0, v[66:67]
	v_lshlrev_b32_e32 v52, 2, v53
	v_mov_b32_e32 v66, v52
	v_mov_b32_e32 v67, v55
	v_lshl_add_u64 v[82:83], v[64:65], 0, v[66:67]
	global_load_dwordx4 v[52:55], v[82:83], off
	s_and_b32 s3, s94, 15
	s_lshl_b32 s0, s3, 6
	s_nop 0
	s_nop 0
	s_nop 0
	s_nop 0
	s_nop 0
	s_nop 0
	s_nop 0
	s_nop 0
	s_nop 0
	s_nop 0
	s_nop 0
	v_and_b32_e32 v80, 15, v1
	v_mov_b32_e32 v3, 0
	s_nop 0
	s_nop 0
	s_nop 0
	s_nop 0
	v_and_b32_e32 v2, 48, v1
	s_nop 0
	s_nop 0
	s_nop 0
	s_nop 0
	s_nop 0
	s_nop 0
	s_nop 0
	s_nop 0
	s_nop 0
	s_nop 0
	s_nop 0
	s_nop 0
	s_nop 0
	s_nop 0
	s_nop 0
	s_nop 0
	s_nop 0
	s_nop 0
	s_nop 0
	s_nop 0
	s_nop 0
	s_nop 0
	s_nop 0
	s_nop 0
	s_nop 0
	s_nop 0
	s_nop 0
	s_nop 0
	s_nop 0
	s_nop 0
	s_nop 0
	s_nop 0
	s_nop 0
	s_lshl_b32 s1, s2, 13
	s_add_i32 s1, s1, 0
	s_nop 0
	s_waitcnt vmcnt(19)
	v_mfma_f32_16x16x32_bf16 v[32:35], v[72:75], v[96:99], 0
	v_mfma_f32_16x16x32_bf16 v[4:7], v[72:75], v[84:87], 0
	v_mfma_f32_16x16x32_bf16 v[48:51], v[88:91], v[96:99], 0
	v_mfma_f32_16x16x32_bf16 v[56:59], v[92:95], v[96:99], 0
	s_nop 0
	s_waitcnt vmcnt(17)
	v_mfma_f32_16x16x32_bf16 v[8:11], v[104:107], v[96:99], 0
	v_mfma_f32_16x16x32_bf16 v[16:19], v[88:91], v[84:87], 0
	v_mfma_f32_16x16x32_bf16 v[20:23], v[92:95], v[84:87], 0
	v_mfma_f32_16x16x32_bf16 v[12:15], v[104:107], v[84:87], 0
	v_mfma_f32_16x16x32_bf16 v[32:35], v[76:79], v[100:103], v[32:35]
	s_nop 0
	s_waitcnt vmcnt(16)
	v_mfma_f32_16x16x32_bf16 v[4:7], v[76:79], v[108:111], v[4:7]
	s_nop 0
	s_waitcnt vmcnt(15)
	v_mfma_f32_16x16x32_bf16 v[28:31], v[112:115], v[100:103], v[48:51]
	s_nop 0
	s_waitcnt vmcnt(14)
	v_mfma_f32_16x16x32_bf16 v[36:39], v[116:119], v[100:103], v[56:59]
	s_nop 0
	s_waitcnt vmcnt(13)
	v_mfma_f32_16x16x32_bf16 v[8:11], v[120:123], v[100:103], v[8:11]
	s_nop 0
	v_mfma_f32_16x16x32_bf16 v[16:19], v[112:115], v[108:111], v[16:19]
	s_nop 0
	s_nop 0
	v_mfma_f32_16x16x32_bf16 v[20:23], v[116:119], v[108:111], v[20:23]
	s_nop 0
	v_mfma_f32_16x16x32_bf16 v[12:15], v[120:123], v[108:111], v[12:15]
	s_nop 0
	s_nop 0
	s_nop 0
	s_nop 0
	s_nop 0
	s_nop 0
	s_nop 0
	s_nop 0
	s_waitcnt vmcnt(11)
	v_mfma_f32_16x16x32_bf16 v[32:35], v[124:127], v[128:131], v[32:35]
	s_nop 0
	s_nop 0
	s_waitcnt vmcnt(10)
	v_mfma_f32_16x16x32_bf16 v[4:7], v[124:127], v[132:135], v[4:7]
	s_nop 0
	s_nop 0
	s_nop 0
	s_nop 0
	s_waitcnt vmcnt(9)
	v_mfma_f32_16x16x32_bf16 v[28:31], v[136:139], v[128:131], v[28:31]
	s_nop 0
	s_waitcnt vmcnt(8)
	v_mfma_f32_16x16x32_bf16 v[36:39], v[140:143], v[128:131], v[36:39]
	s_nop 0
	s_waitcnt vmcnt(5)
	v_mfma_f32_16x16x32_bf16 v[8:11], v[152:155], v[128:131], v[8:11]
	v_lshl_or_b32 v44, v80, 2, s0
	s_movk_i32 s0, 0xa00
	v_mfma_f32_16x16x32_bf16 v[16:19], v[136:139], v[132:135], v[16:19]
	v_mfma_f32_16x16x32_bf16 v[20:23], v[140:143], v[132:135], v[20:23]
	v_lshlrev_b32_e32 v40, 8, v80
	v_add3_u32 v2, s1, v40, v2
	v_mov_b64_e32 v[42:43], s[82:83]
	v_mfma_f32_16x16x32_bf16 v[32:35], v[148:151], v[144:147], v[32:35]
	s_nop 0
	s_waitcnt vmcnt(2)
	v_mfma_f32_16x16x32_bf16 v[28:31], v[68:71], v[144:147], v[28:31]
	s_nop 5
	ds_write_b128 v2, v[32:35]
	s_nop 0
	s_waitcnt vmcnt(1)
	v_mfma_f32_16x16x32_bf16 v[36:39], v[60:63], v[144:147], v[36:39]
	v_mfma_f32_16x16x32_bf16 v[12:15], v[152:155], v[132:135], v[12:15]
	v_mfma_f32_16x16x32_bf16 v[8:11], v[160:163], v[144:147], v[8:11]
	ds_write_b128 v2, v[28:31] offset:64
	s_nop 4
	ds_write_b128 v2, v[36:39] offset:128
	s_nop 0
	ds_write_b128 v2, v[8:11] offset:192
	v_mfma_f32_16x16x32_bf16 v[4:7], v[148:151], v[156:159], v[4:7]
	v_mfma_f32_16x16x32_bf16 v[16:19], v[68:71], v[156:159], v[16:19]
	v_mfma_f32_16x16x32_bf16 v[8:11], v[60:63], v[156:159], v[20:23]
	s_nop 5
	ds_write_b128 v2, v[4:7] offset:4096
	ds_write_b128 v2, v[16:19] offset:4160
	ds_write_b128 v2, v[8:11] offset:4224
	v_ashrrev_i32_e32 v10, 4, v1
	v_mfma_f32_16x16x32_bf16 v[4:7], v[160:163], v[156:159], v[12:15]
	v_lshl_add_u32 v1, v1, 4, 0
	s_nop 6
	ds_write_b128 v2, v[4:7] offset:4288
	s_nop 0
	s_nop 0
	s_nop 0
	s_nop 0
	s_nop 0
	s_nop 0
	s_waitcnt lgkmcnt(0)
	s_barrier
; __device__ __forceinline__ unsigned cvt_pk_bf16(float lo, float hi) { const f32x2_t v = {lo, hi}; const bf16x2_t b = __builtin_convertvector(v, bf16x2_t); return __builtin_bit_cast(unsigned, b); }
; __global__ void __launch_bounds__(NWAVES * 64, 2) fwd_megakernel(Args args) {
;     ...
;             const f32x4 cc = tail_sum(parts, 0, 8, tid);
;             const int r = row0 + (tid >> 4), c = col0 + (tid & 15) * 4;
;             const f32x4 h = cc + *(const f32x4*)(x_sample + (size_t)(r - MP) * DM + c);
;             u32x2 w; w.x = cvt_pk_bf16(h[0], h[1]); w.y = cvt_pk_bf16(h[2], h[3]);
;             *(u32x2*)(HP + (size_t)r * LDHP + c) = w;
;             float ss = (h[0] * h[0] + h[1] * h[1]) + (h[2] * h[2] + h[3] * h[3]);
;             ss += __shfl_xor(ss, 1); ss += __shfl_xor(ss, 2); ss += __shfl_xor(ss, 4); ss += __shfl_xor(ss, 8);
;             if ((tid & 15) == 0) SS[(size_t)r * 16 + tn] = ss;
	s_nop 0
	v_mbcnt_hi_u32_b32 v2, -1, v225
	v_add_u32_e32 v4, s84, v10
	v_and_b32_e32 v10, 64, v2
	v_add_u32_e32 v47, 64, v10
	ds_read_b128 v[10:13], v1
	ds_read_b128 v[14:17], v1 offset:8192
	ds_read_b128 v[18:21], v1 offset:16384
	ds_read_b128 v[22:25], v1 offset:24576
	ds_read_b128 v[26:29], v1 offset:32768
	ds_read_b128 v[30:33], v1 offset:40960
	ds_read_b128 v[34:37], v1 offset:49152
	ds_read_b128 v[38:41], v1 offset:57344
	s_waitcnt lgkmcnt(7)
	v_pk_add_f32 v[12:13], v[12:13], 0 op_sel_hi:[1,0]
	v_pk_add_f32 v[10:11], v[10:11], 0 op_sel_hi:[1,0]
	s_waitcnt lgkmcnt(6)
	v_pk_add_f32 v[12:13], v[12:13], v[16:17]
	v_pk_add_f32 v[10:11], v[10:11], v[14:15]
	s_waitcnt lgkmcnt(5)
	v_pk_add_f32 v[12:13], v[12:13], v[20:21]
	v_pk_add_f32 v[10:11], v[10:11], v[18:19]
	s_waitcnt lgkmcnt(4)
	v_pk_add_f32 v[12:13], v[12:13], v[24:25]
	v_pk_add_f32 v[10:11], v[10:11], v[22:23]
	s_waitcnt lgkmcnt(3)
	v_pk_add_f32 v[12:13], v[12:13], v[28:29]
	v_pk_add_f32 v[10:11], v[10:11], v[26:27]
	s_waitcnt lgkmcnt(2)
	v_pk_add_f32 v[12:13], v[12:13], v[32:33]
	v_pk_add_f32 v[10:11], v[10:11], v[30:31]
	s_waitcnt lgkmcnt(1)
	v_pk_add_f32 v[12:13], v[12:13], v[36:37]
	v_pk_add_f32 v[10:11], v[10:11], v[34:35]
	s_waitcnt lgkmcnt(0)
	v_pk_add_f32 v[12:13], v[12:13], v[40:41]
	v_pk_add_f32 v[10:11], v[10:11], v[38:39]
	v_xor_b32_e32 v5, 1, v2
	v_cmp_lt_i32_e32 vcc, v5, v47
	v_xor_b32_e32 v45, 2, v2
	v_xor_b32_e32 v46, 4, v2
	v_cndmask_b32_e32 v5, v2, v5, vcc
	v_lshlrev_b32_e32 v5, 2, v5
	v_cmp_lt_i32_e32 vcc, v45, v47
	s_nop 0
	s_waitcnt vmcnt(0)
	v_pk_add_f32 v[8:9], v[12:13], v[54:55]
	v_pk_add_f32 v[6:7], v[10:11], v[52:53]
	v_mul_f32_e32 v10, v9, v9
	v_mul_f32_e32 v1, v7, v7
	v_fmac_f32_e32 v1, v6, v6
	v_fmac_f32_e32 v10, v8, v8
	v_add_f32_e32 v1, v1, v10
	ds_bpermute_b32 v5, v5, v1
	v_cndmask_b32_e32 v10, v2, v45, vcc
	v_lshlrev_b32_e32 v10, 2, v10
	v_cmp_lt_i32_e32 vcc, v46, v47
	v_xor_b32_e32 v12, 8, v2
	s_waitcnt lgkmcnt(0)
	v_add_f32_e32 v1, v1, v5
	ds_bpermute_b32 v5, v10, v1
	v_cndmask_b32_e32 v13, v2, v46, vcc
	v_lshlrev_b32_e32 v13, 2, v13
	v_cmp_lt_i32_e32 vcc, v12, v47
	v_mad_i64_i32 v[10:11], s[0:1], v4, s0, v[42:43]
	s_waitcnt lgkmcnt(0)
	v_add_f32_e32 v1, v1, v5
	ds_bpermute_b32 v5, v13, v1
	v_cndmask_b32_e32 v2, v2, v12, vcc
	v_lshlrev_b32_e32 v2, 2, v2
	v_cvt_pk_bf16_f32 v12, v6, v7
	v_cvt_pk_bf16_f32 v13, v8, v9
	s_waitcnt lgkmcnt(0)
	v_add_f32_e32 v1, v1, v5
	ds_bpermute_b32 v6, v2, v1
	v_lshlrev_b32_e32 v2, 1, v44
	v_lshl_add_u64 v[2:3], v[10:11], 0, v[2:3]
	v_cmp_eq_u32_e32 vcc, 0, v80
	global_store_dwordx2 v[2:3], v[12:13], off
	s_and_saveexec_b64 s[0:1], vcc
	s_cbranch_execz .LBB0_887
	s_lshl_b32 s2, s3, 2
	v_ashrrev_i32_e32 v5, 31, v4
	s_add_u32 s2, s8, s2
	s_addc_u32 s3, s9, 0
	v_lshlrev_b64 v[2:3], 6, v[4:5]
	v_lshl_add_u64 v[2:3], s[2:3], 0, v[2:3]
	s_waitcnt lgkmcnt(0)
	v_add_f32_e32 v1, v1, v6
	global_store_dword v[2:3], v1, off

; #define LAS __attribute__((address_space(3)))
; __device__ __forceinline__ int permrow(int n) { return (n & ~255) | ((((n >> 5) & 1) * 128) + (((n >> 6) & 3) * 32) + (n & 31)); }
; template <int KSTEPS>
; __device__ __forceinline__ void tail_partial(const bf16_t* A, int lda, const bf16_t* Bt, int ldb, int col0, LAS float* part, int lane) {
;     const int fr = lane & 15, fq = lane >> 4;
;     f32x4 acc[2][4];
; #pragma unroll
;     for (int m = 0; m < 2; ++m)
; #pragma unroll
;         for (int n = 0; n < 4; ++n) acc[m][n] = (f32x4){0.f, 0.f, 0.f, 0.f};
;     const bf16_t* ap = A + (size_t)fr * lda + 8 * fq;
;     const bf16_t* bp[4];
; #pragma unroll
;     for (int n = 0; n < 4; ++n) bp[n] = Bt + (size_t)permrow(col0 + 16 * n + fr) * ldb + 8 * fq;
; #pragma unroll
;     for (int ks = 0; ks < KSTEPS; ++ks) {
;         bf16x8 a[2], b[4];
; #pragma unroll
;         for (int m = 0; m < 2; ++m) a[m] = *(const bf16x8*)(ap + (size_t)(16 * m) * lda + 32 * ks);
; #pragma unroll
;         for (int n = 0; n < 4; ++n) b[n] = *(const bf16x8*)(bp[n] + 32 * ks);
; __global__ void __launch_bounds__(NWAVES * 64, 2) fwd_megakernel(Args args) {
;     ...
;             const int tm = bx >> 4, tn = bx & 15, row0 = MP + 32 * tm, col0 = 64 * tn;
;             LAS float* parts = (LAS float*)lds;
;             tail_partial<1>(HP + (size_t)row0 * LDHP + 1024 + wave * 32, LDHP, WGP_t + 1024 + wave * 32, LDHP, col0, parts + wave * 2048, lane);
;             __syncthreads();
;             const f32x4 ple = tail_sum(parts, 0, 8, tid);
;             __syncthreads();
;             tail_partial<4>(HP + (size_t)row0 * LDHP + wave * 128, LDHP, WGP_t + wave * 128, LDHP, col0, parts + wave * 2048, lane);
.LBB0_970:
	s_or_b64 exec, exec, s[0:1]
	s_and_b64 vcc, exec, s[38:39]
	s_movk_i32 s26, 0x82
	s_waitcnt lgkmcnt(0)
	s_barrier
	s_cbranch_vccnz .LBB0_972
	v_mov_b32_e32 v59, v0
	s_mul_i32 s12, s84, 0xa00
	v_readfirstlane_b32 s13, v59
	s_ashr_i32 s14, s13, 6
	s_mul_hi_i32 s13, s84, 0xa00
	s_add_u32 s15, s82, s12
	s_addc_u32 s12, s83, s13
	s_lshl_b32 s18, s14, 5
	s_ashr_i32 s19, s18, 31
	s_lshl_b64 s[20:21], s[18:19], 1
	s_add_u32 s18, s15, s20
	s_addc_u32 s19, s12, s21
	v_readlane_b32 s12, v254, 17
	v_readlane_b32 s13, v254, 18
	s_add_u32 s24, s12, s20
	s_addc_u32 s25, s13, s21
	v_and_b32_e32 v76, 48, v59
	v_mov_b32_e32 v77, 0
	v_lshl_add_u64 v[78:79], s[24:25], 0, v[76:77]
	s_lshr_b32 s12, s23, 1
	v_and_b32_e32 v80, 15, v59
	s_and_b32 s13, s12, 0x60
	s_and_b32 s12, s23, 0x300
	v_mul_u32_u24_e32 v81, 0x500, v80
	s_or_b32 s15, s12, s13
	v_or_b32_e32 v82, s15, v80
	v_lshlrev_b32_e32 v84, 1, v81
	v_mov_b32_e32 v85, v77
	s_movk_i32 s12, 0xa00
	v_mov_b32_e32 v80, 0x5a000
	v_mul_u32_u24_e32 v86, 0xa00, v82
	v_mov_b32_e32 v87, v77
	v_lshl_add_u64 v[88:89], s[18:19], 0, v[84:85]
	v_mov_b32_e32 v91, v77
	v_mad_u32_u24 v90, v82, s12, v80
	v_lshl_add_u64 v[80:81], v[78:79], 0, v[86:87]
	v_lshl_add_u64 v[86:87], v[88:89], 0, v[76:77]
	s_mov_b32 s13, 0xa000
	v_lshl_add_u64 v[88:89], v[78:79], 0, v[90:91]
	global_load_dwordx4 v[92:95], v[86:87], off offset:2048
	global_load_dwordx4 v[96:99], v[80:81], off
	s_mov_b32 s15, 0x50000
	global_load_dwordx4 v[100:103], v[88:89], off
	v_add_co_u32_e32 v78, vcc, s13, v86
	s_nop 1
	s_mul_hi_i32 s17, s14, 0xc0
	v_addc_co_u32_e32 v79, vcc, 0, v87, vcc
	s_nop 1
	v_add_co_u32_e32 v86, vcc, s13, v80
	s_nop 1
	global_load_dwordx4 v[88:91], v[78:79], off offset:2048
	v_addc_co_u32_e32 v87, vcc, 0, v81, vcc
	s_nop 1
	v_add_co_u32_e32 v78, vcc, s15, v80
	s_nop 1
	global_load_dwordx4 v[104:107], v[86:87], off
	v_addc_co_u32_e32 v79, vcc, 0, v81, vcc
	s_nop 1
	global_load_dwordx4 v[108:111], v[78:79], off
	s_mul_i32 s20, s14, 0xc0
	s_lshl_b32 s24, s14, 7
	s_ashr_i32 s25, s24, 31
	s_add_u32 s28, s18, s20
	s_addc_u32 s29, s19, s17
	s_lshl_b64 s[18:19], s[24:25], 1
	s_add_u32 s20, s86, s18
	v_mul_u32_u24_e32 v78, 0x500, v82
	s_addc_u32 s21, s87, s19
	v_mov_b32_e32 v81, v77
	v_lshlrev_b32_e32 v80, 1, v78
	v_lshl_add_u64 v[78:79], s[20:21], 0, v[76:77]
	v_lshl_add_u64 v[82:83], v[78:79], 0, v[80:81]
	v_add_co_u32_e32 v86, vcc, s13, v82
	s_nop 1
	v_addc_co_u32_e32 v87, vcc, 0, v83, vcc
	s_nop 1
	v_lshl_add_u64 v[112:113], s[28:29], 0, v[84:85]
	v_add_co_u32_e32 v84, vcc, s15, v82
	s_nop 1
	v_add_u32_e32 v116, 0x5a000, v80
	v_lshl_add_u64 v[118:119], v[112:113], 0, v[76:77]
	v_addc_co_u32_e32 v85, vcc, 0, v83, vcc
	s_nop 1
	v_mov_b32_e32 v112, v116
	v_mov_b32_e32 v113, v81
	v_lshl_add_u64 v[120:121], v[78:79], 0, v[112:113]
	v_add_co_u32_e32 v78, vcc, s13, v118
	s_nop 1
	s_mov_b64 s[14:15], 0xa000
	v_addc_co_u32_e32 v79, vcc, 0, v119, vcc
	s_nop 1
	v_lshl_add_u64 v[80:81], v[82:83], 0, s[14:15]
	s_mov_b64 s[14:15], 0x50000
	v_lshl_add_u64 v[112:113], v[82:83], 0, s[14:15]
	v_ashrrev_i32_e32 v76, 4, v59
	v_lshlrev_b32_e32 v116, 2, v59
	v_and_or_b32 v59, v116, 60, s22
	global_load_dwordx4 v[124:127], v[118:119], off
	global_load_dwordx4 v[128:131], v[82:83], off
	global_load_dwordx4 v[132:135], v[86:87], off
	global_load_dwordx4 v[136:139], v[84:85], off
	global_load_dwordx4 v[84:87], v[118:119], off offset:64
	global_load_dwordx4 v[140:143], v[82:83], off offset:64
	global_load_dwordx4 v[144:147], v[120:121], off
	global_load_dwordx4 v[148:151], v[120:121], off offset:64
	global_load_dwordx4 v[152:155], v[78:79], off
	global_load_dwordx4 v[156:159], v[78:79], off offset:64
	global_load_dwordx4 v[160:163], v[80:81], off offset:128
	global_load_dwordx4 v[164:167], v[80:81], off offset:64
	global_load_dwordx4 v[168:171], v[112:113], off offset:64
	global_load_dwordx4 v[172:175], v[80:81], off offset:192
	global_load_dwordx4 v[176:179], v[82:83], off offset:128
	global_load_dwordx4 v[180:183], v[112:113], off offset:128
	global_load_dwordx4 v[184:187], v[118:119], off offset:128
	global_load_dwordx4 v[188:191], v[120:121], off offset:128
	global_load_dwordx4 v[192:195], v[118:119], off offset:192
	global_load_dwordx4 v[116:119], v[82:83], off offset:192
	global_load_dwordx4 v[80:83], v[112:113], off offset:192
	global_load_dwordx4 v[196:199], v[78:79], off offset:128
	global_load_dwordx4 v[200:203], v[120:121], off offset:192
	global_load_dwordx4 v[120:123], v[78:79], off offset:192
	v_add_u32_e32 v78, s84, v76
	v_ashrrev_i32_e32 v79, 31, v78
	v_lshlrev_b64 v[112:113], 6, v[78:79]
	v_lshl_add_u64 v[204:205], s[8:9], 0, v[112:113]
	v_lshlrev_b32_e32 v76, 1, v59
	global_load_dwordx4 v[208:211], v[204:205], off
	global_load_dwordx4 v[212:215], v[204:205], off offset:16
	global_load_dwordx4 v[216:219], v[204:205], off offset:32
	global_load_dwordx4 v[220:223], v[204:205], off offset:48
	v_mov_b64_e32 v[112:113], s[82:83]
	v_mad_i64_i32 v[204:205], s[14:15], v78, s12, v[112:113]
	v_mov_b32_e32 v78, v76
	v_mov_b32_e32 v79, v77
	v_lshl_add_u64 v[112:113], v[204:205], 0, v[78:79]
	global_load_dwordx2 v[76:77], v[112:113], off
	v_mov_b32_e32 v1, v0
	s_nop 0
	v_readfirstlane_b32 s0, v1
	s_ashr_i32 s4, s0, 6
	s_nop 0
	s_nop 0
	s_nop 0
	s_nop 0
	s_nop 0
	s_nop 0
	s_nop 0
	s_nop 0
	s_nop 0
	s_nop 0
	s_nop 0
	s_nop 0
	v_and_b32_e32 v34, 48, v1
	v_mov_b32_e32 v35, 0
	s_nop 0
	s_nop 0
	v_and_b32_e32 v36, 15, v1
	s_nop 0
	s_nop 0
	s_nop 0
	s_nop 0
	s_nop 0
	s_nop 0
	s_nop 0
	s_nop 0
	s_nop 0
	s_nop 0
	s_nop 0
	s_nop 0
	s_nop 0
	s_nop 0
	s_nop 0
	s_nop 0
	s_nop 0
	s_nop 0
	s_nop 0
	s_nop 0
	s_nop 0
	s_nop 0
	s_nop 0
	s_nop 0
	s_nop 0
	s_nop 0
	s_nop 0
	s_nop 0
	s_nop 0
	s_nop 0
	s_nop 0
	s_nop 0
	s_nop 0
	s_nop 0
	s_nop 0
	s_nop 0
	s_lshl_b32 s5, s4, 13
	s_nop 0
	s_add_i32 s11, s5, 0
	s_nop 0
	s_nop 0
	s_nop 0
	s_nop 0
	s_nop 0
	s_nop 0
	s_nop 0
	s_nop 0
	s_nop 0
	s_nop 0
	s_nop 0
	s_nop 0
	v_lshlrev_b32_e32 v36, 8, v36
	s_nop 0
	s_nop 0
	s_nop 0
	s_nop 0
	s_nop 0
	v_lshl_add_u32 v114, v1, 4, 0
	v_add3_u32 v115, s11, v36, v34
	s_nop 0
	s_nop 0
	s_nop 0
	s_nop 0
	s_nop 0
	s_nop 0
	s_nop 0
	s_nop 0
	s_nop 0
	s_nop 0
	v_ashrrev_i32_e32 v34, 4, v1
	v_lshlrev_b32_e32 v1, 2, v1
	v_and_or_b32 v1, v1, 60, s22
	s_nop 0
	s_waitcnt vmcnt(33)
; #define LAS __attribute__((address_space(3)))
; template <int KSTEPS>
; __device__ __forceinline__ void tail_partial(const bf16_t* A, int lda, const bf16_t* Bt, int ldb, int col0, LAS float* part, int lane) {
;     ...
;     for (int ks = 0; ks < KSTEPS; ++ks) {
;         bf16x8 a[2], b[4];
; #pragma unroll
;         for (int m = 0; m < 2; ++m) a[m] = *(const bf16x8*)(ap + (size_t)(16 * m) * lda + 32 * ks);
; #pragma unroll
;         for (int n = 0; n < 4; ++n) b[n] = *(const bf16x8*)(bp[n] + 32 * ks);
; #pragma unroll
;         for (int m = 0; m < 2; ++m)
; #pragma unroll
;             for (int n = 0; n < 4; ++n) acc[m][n] = __builtin_amdgcn_mfma_f32_16x16x32_bf16(b[n], a[m], acc[m][n], 0, 0, 0);
;     }
; #pragma unroll
;     for (int m = 0; m < 2; ++m)
; #pragma unroll
;         for (int n = 0; n < 4; ++n) *(LAS f32x4*)(part + (16 * m + fr) * 64 + 16 * n + 4 * fq) = acc[m][n];
; __global__ void __launch_bounds__(NWAVES * 64, 2) fwd_megakernel(Args args) {
;     ...
;             tail_partial<1>(HP + (size_t)row0 * LDHP + 1024 + wave * 32, LDHP, WGP_t + 1024 + wave * 32, LDHP, col0, parts + wave * 2048, lane);
;             __syncthreads();
;             const f32x4 ple = tail_sum(parts, 0, 8, tid);
;             __syncthreads();
;             tail_partial<4>(HP + (size_t)row0 * LDHP + wave * 128, LDHP, WGP_t + wave * 128, LDHP, col0, parts + wave * 2048, lane);
;             __syncthreads();
;             const f32x4 cc = tail_sum(parts, 0, 8, tid);
	v_mfma_f32_16x16x32_bf16 v[22:25], v[96:99], v[92:95], 0
	s_movk_i32 s26, 0x80
	s_nop 0
	s_waitcnt vmcnt(32)
	v_mfma_f32_16x16x32_bf16 v[30:33], v[100:103], v[92:95], 0
	s_nop 0
	s_waitcnt vmcnt(31)
	v_mfma_f32_16x16x32_bf16 v[2:5], v[96:99], v[88:91], 0
	v_mfma_f32_16x16x32_bf16 v[10:13], v[100:103], v[88:91], 0
	s_nop 0
	s_waitcnt vmcnt(30)
	v_mfma_f32_16x16x32_bf16 v[36:39], v[104:107], v[92:95], 0
	s_nop 0
	s_waitcnt vmcnt(29)
	v_mfma_f32_16x16x32_bf16 v[6:9], v[108:111], v[92:95], 0
	v_mfma_f32_16x16x32_bf16 v[18:21], v[104:107], v[88:91], 0
	v_mfma_f32_16x16x32_bf16 v[14:17], v[108:111], v[88:91], 0
	ds_write_b128 v115, v[22:25]
	ds_write_b128 v115, v[30:33] offset:192
	ds_write_b128 v115, v[2:5] offset:4096
	ds_write_b128 v115, v[10:13] offset:4288
	ds_write_b128 v115, v[36:39] offset:64
	s_nop 0
	ds_write_b128 v115, v[6:9] offset:128
	ds_write_b128 v115, v[18:21] offset:4160
	ds_write_b128 v115, v[14:17] offset:4224
	s_waitcnt lgkmcnt(0)
	s_barrier
	ds_read_b128 v[30:33], v114
	ds_read_b128 v[26:29], v114 offset:8192
	ds_read_b128 v[22:25], v114 offset:16384
	ds_read_b128 v[18:21], v114 offset:24576
	ds_read_b128 v[14:17], v114 offset:32768
	ds_read_b128 v[10:13], v114 offset:40960
	ds_read_b128 v[6:9], v114 offset:49152
	ds_read_b128 v[2:5], v114 offset:57344
	s_waitcnt lgkmcnt(0)
	s_barrier
	s_nop 0
	s_nop 0
	v_pk_add_f32 v[32:33], v[32:33], 0 op_sel_hi:[1,0]
	s_nop 0
	s_nop 0
	s_nop 0
	s_nop 0
	s_nop 0
	s_nop 0
	s_nop 0
	s_nop 0
	s_nop 0
	v_pk_add_f32 v[30:31], v[30:31], 0 op_sel_hi:[1,0]
	v_pk_add_f32 v[28:29], v[32:33], v[28:29]
	v_pk_add_f32 v[26:27], v[30:31], v[26:27]
	v_pk_add_f32 v[24:25], v[28:29], v[24:25]
	v_pk_add_f32 v[22:23], v[26:27], v[22:23]
	v_pk_add_f32 v[20:21], v[24:25], v[20:21]
	v_pk_add_f32 v[18:19], v[22:23], v[18:19]
	v_pk_add_f32 v[16:17], v[20:21], v[16:17]
	v_pk_add_f32 v[14:15], v[18:19], v[14:15]
	v_pk_add_f32 v[12:13], v[16:17], v[12:13]
	v_pk_add_f32 v[10:11], v[14:15], v[10:11]
	v_pk_add_f32 v[8:9], v[12:13], v[8:9]
	v_pk_add_f32 v[6:7], v[10:11], v[6:7]
	s_nop 0
	s_waitcnt vmcnt(25)
	v_mfma_f32_16x16x32_bf16 v[72:75], v[136:139], v[124:127], 0
	s_nop 0
	v_mfma_f32_16x16x32_bf16 v[60:63], v[128:131], v[124:127], 0
	v_mfma_f32_16x16x32_bf16 v[64:67], v[132:135], v[124:127], 0
	s_nop 0
	s_waitcnt vmcnt(22)
	v_mfma_f32_16x16x32_bf16 v[36:39], v[144:147], v[124:127], 0
	s_nop 0
	s_waitcnt vmcnt(20)
	v_mfma_f32_16x16x32_bf16 v[40:43], v[128:131], v[152:155], 0
	v_mfma_f32_16x16x32_bf16 v[44:47], v[132:135], v[152:155], 0
	v_mfma_f32_16x16x32_bf16 v[48:51], v[136:139], v[152:155], 0
	v_mfma_f32_16x16x32_bf16 v[68:71], v[144:147], v[152:155], 0
	s_nop 0
	s_nop 0
	s_nop 0
	v_mfma_f32_16x16x32_bf16 v[60:63], v[140:143], v[84:87], v[60:63]
	s_nop 0
	s_waitcnt vmcnt(17)
	v_mfma_f32_16x16x32_bf16 v[64:67], v[164:167], v[84:87], v[64:67]
	s_nop 0
	s_waitcnt vmcnt(16)
	v_mfma_f32_16x16x32_bf16 v[72:75], v[168:171], v[84:87], v[72:75]
	v_mfma_f32_16x16x32_bf16 v[36:39], v[148:151], v[84:87], v[36:39]
	s_nop 0
	v_mfma_f32_16x16x32_bf16 v[44:47], v[164:167], v[156:159], v[44:47]
	s_nop 0
	v_mfma_f32_16x16x32_bf16 v[40:43], v[140:143], v[156:159], v[40:43]
	s_nop 0
	v_mfma_f32_16x16x32_bf16 v[48:51], v[168:171], v[156:159], v[48:51]
	v_mfma_f32_16x16x32_bf16 v[68:71], v[148:151], v[156:159], v[68:71]
	s_nop 0
	s_nop 0
	s_nop 0
	s_nop 0
	s_nop 0
	s_nop 0
	s_waitcnt vmcnt(12)
	v_mfma_f32_16x16x32_bf16 v[60:63], v[176:179], v[184:187], v[60:63]
	s_nop 0
	s_nop 0
	s_nop 0
	v_mfma_f32_16x16x32_bf16 v[64:67], v[160:163], v[184:187], v[64:67]
	v_mfma_f32_16x16x32_bf16 v[72:75], v[180:183], v[184:187], v[72:75]
	s_nop 0
	s_waitcnt vmcnt(11)
	v_mfma_f32_16x16x32_bf16 v[36:39], v[188:191], v[184:187], v[36:39]
	s_nop 0
	s_nop 0
	s_waitcnt vmcnt(7)
	v_mfma_f32_16x16x32_bf16 v[40:43], v[176:179], v[196:199], v[40:43]
	v_mfma_f32_16x16x32_bf16 v[44:47], v[160:163], v[196:199], v[44:47]
	v_mfma_f32_16x16x32_bf16 v[48:51], v[180:183], v[196:199], v[48:51]
	v_mfma_f32_16x16x32_bf16 v[52:55], v[188:191], v[196:199], v[68:71]
	v_mfma_f32_16x16x32_bf16 v[60:63], v[116:119], v[192:195], v[60:63]
	v_mfma_f32_16x16x32_bf16 v[68:71], v[80:83], v[192:195], v[72:75]
	s_nop 2
	v_add_u32_e32 v72, s84, v34
	v_mfma_f32_16x16x32_bf16 v[64:67], v[172:175], v[192:195], v[64:67]
	v_ashrrev_i32_e32 v73, 31, v72
	s_nop 0
	s_nop 0
	s_nop 0
	s_waitcnt vmcnt(6)
	v_mfma_f32_16x16x32_bf16 v[36:39], v[200:203], v[192:195], v[36:39]
	s_nop 0
	s_nop 0
	s_waitcnt vmcnt(5)
	v_mfma_f32_16x16x32_bf16 v[40:43], v[116:119], v[120:123], v[40:43]
	v_mfma_f32_16x16x32_bf16 v[44:47], v[172:175], v[120:123], v[44:47]
	v_mfma_f32_16x16x32_bf16 v[48:51], v[80:83], v[120:123], v[48:51]
	v_mfma_f32_16x16x32_bf16 v[52:55], v[200:203], v[120:123], v[52:55]
	ds_write_b128 v115, v[60:63]
	ds_write_b128 v115, v[64:67] offset:64
	ds_write_b128 v115, v[68:71] offset:128
	ds_write_b128 v115, v[36:39] offset:192
	s_nop 0
	ds_write_b128 v115, v[40:43] offset:4096
	ds_write_b128 v115, v[44:47] offset:4160
	ds_write_b128 v115, v[48:51] offset:4224
	ds_write_b128 v115, v[52:55] offset:4288
	s_waitcnt lgkmcnt(0)
	s_barrier
; __device__ __forceinline__ float bf_lo(unsigned w) { return __uint_as_float(w << 16); }
; __device__ __forceinline__ float bf_hi(unsigned w) { return __uint_as_float(w & 0xffff0000u); }
; __device__ __forceinline__ float sigmoidf_(float x) { return fast_rcp(1.f + fast_exp2(-LOG2E * x)); }
; __global__ void __launch_bounds__(NWAVES * 64, 2) fwd_megakernel(Args args) {
;     ...
;             const f32x4 cc = tail_sum(parts, 0, 8, tid);
;             const int r = row0 + (tid >> 4), c = col0 + (tid & 15) * 4;
;             const f32x4* sp = (const f32x4*)(SS + (size_t)r * 16);
;             const f32x4 s0 = sp[0], s1 = sp[1], s2 = sp[2], s3 = sp[3];
;             const float st = ((s0[0] + s0[1]) + (s0[2] + s0[3])) + ((s1[0] + s1[1]) + (s1[2] + s1[3])) + ((s2[0] + s2[1]) + (s2[2] + s2[3])) + ((s3[0] + s3[1]) + (s3[2] + s3[3]));
;             const float rstd = rsqrtf(st * (1.f / DM) + EPS);
;             const u32x2 hw = *(const u32x2*)(HP + (size_t)r * LDHP + c);
;             f32x4 y;
;             y[0] = bf_lo(hw.x) + sigmoidf_(rstd * cc[0]) * ple[0]; y[1] = bf_hi(hw.x) + sigmoidf_(rstd * cc[1]) * ple[1];
;             y[2] = bf_lo(hw.y) + sigmoidf_(rstd * cc[2]) * ple[2]; y[3] = bf_hi(hw.y) + sigmoidf_(rstd * cc[3]) * ple[3];
;             *(f32x4*)(out + (size_t)r * DM + c) = y;
	s_nop 0
	s_nop 0
	s_nop 0
	s_nop 0
	s_nop 0
	s_nop 0
	s_nop 0
	s_nop 0
	v_lshlrev_b64 v[54:55], 12, v[72:73]
	v_lshl_add_u64 v[54:55], s[60:61], 0, v[54:55]
	v_lshlrev_b32_e32 v34, 2, v1
	v_lshl_add_u64 v[34:35], v[54:55], 0, v[34:35]
	v_pk_add_f32 v[54:55], v[8:9], v[4:5]
	v_pk_add_f32 v[56:57], v[6:7], v[2:3]
	ds_read_b128 v[2:5], v114
	ds_read_b128 v[6:9], v114 offset:8192
	ds_read_b128 v[10:13], v114 offset:16384
	ds_read_b128 v[14:17], v114 offset:24576
	ds_read_b128 v[18:21], v114 offset:32768
	ds_read_b128 v[22:25], v114 offset:40960
	ds_read_b128 v[26:29], v114 offset:49152
	ds_read_b128 v[30:33], v114 offset:57344
	s_waitcnt lgkmcnt(7)
	v_pk_add_f32 v[4:5], v[4:5], 0 op_sel_hi:[1,0]
	v_pk_add_f32 v[2:3], v[2:3], 0 op_sel_hi:[1,0]
	s_waitcnt lgkmcnt(6)
	v_pk_add_f32 v[4:5], v[4:5], v[8:9]
	v_pk_add_f32 v[2:3], v[2:3], v[6:7]
	s_waitcnt lgkmcnt(5)
	v_pk_add_f32 v[4:5], v[4:5], v[12:13]
	v_pk_add_f32 v[2:3], v[2:3], v[10:11]
	v_mov_b32_e32 v58, 0x358637bd
	s_mov_b32 s0, 0x800000
	s_waitcnt lgkmcnt(4)
	v_pk_add_f32 v[4:5], v[4:5], v[16:17]
	v_pk_add_f32 v[2:3], v[2:3], v[14:15]
	s_waitcnt lgkmcnt(3)
	v_pk_add_f32 v[4:5], v[4:5], v[20:21]
	v_pk_add_f32 v[2:3], v[2:3], v[18:19]
	s_waitcnt lgkmcnt(2)
	v_pk_add_f32 v[4:5], v[4:5], v[24:25]
	v_pk_add_f32 v[2:3], v[2:3], v[22:23]
	s_waitcnt lgkmcnt(1)
	v_pk_add_f32 v[4:5], v[4:5], v[28:29]
	v_pk_add_f32 v[2:3], v[2:3], v[26:27]
	s_waitcnt lgkmcnt(0)
	v_pk_add_f32 v[4:5], v[4:5], v[32:33]
	v_pk_add_f32 v[2:3], v[2:3], v[30:31]
	s_nop 0
	s_waitcnt vmcnt(4)
	v_mov_b32_e32 v6, v209
	v_mov_b32_e32 v7, v210
	v_mov_b32_e32 v37, v211
	s_nop 0
	s_waitcnt vmcnt(3)
	v_mov_b32_e32 v8, v213
	v_mov_b32_e32 v9, v214
	v_mov_b32_e32 v41, v215
	v_mov_b32_e32 v36, v208
	v_pk_add_f32 v[6:7], v[6:7], v[36:37]
	v_mov_b32_e32 v40, v212
	v_pk_add_f32 v[8:9], v[8:9], v[40:41]
	v_pk_add_f32 v[6:7], v[6:7], v[6:7] op_sel:[0,1] op_sel_hi:[1,0]
	v_pk_add_f32 v[8:9], v[8:9], v[8:9] op_sel:[0,1] op_sel_hi:[1,0]
	s_nop 0
	s_waitcnt vmcnt(2)
	v_add_f32_e32 v10, v216, v217
	v_add_f32_e32 v12, v218, v219
	s_nop 0
	s_waitcnt vmcnt(1)
	v_mov_b32_e32 v11, v222
	v_mov_b32_e32 v13, v223
	v_mov_b32_e32 v7, v220
	v_mov_b32_e32 v9, v221
	v_pk_add_f32 v[10:11], v[10:11], v[12:13]
	v_pk_add_f32 v[6:7], v[6:7], v[8:9]
	s_nop 0
	s_waitcnt vmcnt(0)
	v_and_b32_e32 v9, 0xffff0000, v77
	v_pk_add_f32 v[6:7], v[6:7], v[10:11]
	s_nop 0
	v_add_f32_e32 v1, v6, v7
	v_fmac_f32_e32 v58, 0x3a800000, v1
	v_mul_f32_e32 v1, 0x4b800000, v58
	v_cmp_gt_f32_e32 vcc, s0, v58
	v_lshlrev_b32_e32 v6, 16, v76
	v_and_b32_e32 v7, 0xffff0000, v76
	v_cndmask_b32_e32 v1, v58, v1, vcc
	v_rsq_f32_e32 v1, v1
	s_nop 0
	v_mul_f32_e32 v8, 0x45800000, v1
	v_cndmask_b32_e32 v1, v1, v8, vcc
	v_mul_f32_e32 v2, v2, v1
	v_mul_f32_e32 v3, v3, v1
	v_mul_f32_e32 v4, v4, v1
	v_mul_f32_e32 v1, v5, v1
	v_mul_f32_e32 v2, 0xbfb8aa3b, v2
	v_mul_f32_e32 v3, 0xbfb8aa3b, v3
	v_mul_f32_e32 v4, 0xbfb8aa3b, v4
	v_mul_f32_e32 v1, 0xbfb8aa3b, v1
	v_exp_f32_e32 v2, v2
	v_exp_f32_e32 v3, v3
	v_exp_f32_e32 v4, v4
	v_exp_f32_e32 v1, v1
	v_add_f32_e32 v2, 1.0, v2
	v_add_f32_e32 v3, 1.0, v3
	v_add_f32_e32 v4, 1.0, v4
	v_add_f32_e32 v1, 1.0, v1
	v_rcp_f32_e32 v2, v2
	v_rcp_f32_e32 v3, v3
	v_rcp_f32_e32 v4, v4
	v_rcp_f32_e32 v5, v1
	v_lshlrev_b32_e32 v8, 16, v77
	v_pk_fma_f32 v[2:3], v[56:57], v[2:3], v[6:7]
	v_pk_fma_f32 v[4:5], v[54:55], v[4:5], v[8:9]
	global_store_dwordx4 v[34:35], v[2:5], off
	s_barrier
